# static priority raise moved to the older wave half (waves 0-3) in GEMM and attention phases, A/B against the younger-half raise
# baseline (speedup 1.0000x reference)
; __device__ __forceinline__ int fresh_tid() { int t = threadIdx.x; asm volatile("" : "+v"(t)); return t; }
; #define PG8_STAGE(bufoff, gbase, voff) do { _Pragma("unroll") for (int _i = 0; _i < 2; ++_i) \
;         __builtin_amdgcn_global_load_lds((const unsigned*)((const char*)(gbase) + (voff)[_i]), (LAS unsigned*)(lds + (bufoff) + ldsw + _i * 8192), 16, 0, 0); } while (0)
; #define PG8_WAIT_V(n) asm volatile("s_waitcnt vmcnt(" #n ")" ::: "memory")
; #define PG8_BAR __builtin_amdgcn_s_barrier()
; template <class Epi>
; __device__ __forceinline__ void gemm_phase(LAS unsigned char* lds, const Gemm g, const StaticOrder& S, const Epi& E) {
;     const int tid = fresh_tid(), wid = __builtin_amdgcn_readfirstlane(tid >> 6), lane = tid & 63, wr = wid >> 2, wc = wid & 3, fr = lane & 15, fq = lane >> 4;
;     const int K = g.K, nt = K / BK;
;     unsigned voffA[2], voffB[2];
; #pragma unroll
;     for (int i = 0; i < 2; ++i) { int R, C; stage_rc(tid * 16 + i * 8192, R, C); const int Rb = (R & ~31) + perm32(R & 31);
;         voffA[i] = (unsigned)(R * K + C) * 2u; voffB[i] = (unsigned)(Rb * K + C) * 2u; }
;     const size_t kstep = (size_t)(BK * 2);
;     const size_t hstep = (size_t)HALF * K * 2;
;     const size_t tstep = 2 * hstep;
;     const unsigned ldsw = (unsigned)wid * 1024u;
;     const int aoff = lds_byte(wr * 64 + fr, fq * 8), boff = lds_byte(wc * 32 + fr, fq * 8);
;     ...
;     Unit cur, nxt; int ui = 0;
;     if (!S.next(0, cur)) return;
;     f32x4 acc[2][2][4][2];
; #pragma unroll
;     for (int a = 0; a < 2; ++a)
; #pragma unroll
;         for (int b = 0; b < 2; ++b)
; #pragma unroll
;             for (int m = 0; m < 4; ++m)
; #pragma unroll
;                 for (int n = 0; n < 2; ++n) acc[a][b][m][n] = (f32x4){0.f, 0.f, 0.f, 0.f};
;     bf16x8 At[4][2], B0[2][2], B1[2][2];
;     const char* cA = (const char*)g.A + (size_t)cur.pm * tstep; const char* cB = (const char*)g.Bt + (size_t)cur.pn * tstep;
;     PG8_STAGE(PG8_SB(0, 0), cB, voffB); PG8_STAGE(PG8_SA(0, 0), cA, voffA); PG8_STAGE(PG8_SB(0, 1), cB + hstep, voffB); PG8_STAGE(PG8_SA(0, 1), cA + hstep, voffA);
;     if (wr == 1) PG8_BAR;
;     PG8_WAIT_V(4); PG8_BAR;
.LBB0_196:
	v_readlane_b32 s8, v232, 0
	s_lshl_b32 s3, s8, 13
	s_add_u32 s4, s16, 0xbb50000
	s_addc_u32 s5, s17, 0
	s_lshl_b32 s61, s60, 11
	s_mul_i32 s9, s8, 0x6000000
	s_or_b32 s8, s3, s61
	v_writelane_b32 v232, s3, 6
	s_lshl_b32 s3, s8, 12
	s_add_u32 s97, s4, s3
	v_writelane_b32 v232, s4, 7
	s_addc_u32 s94, s5, 0
	s_lshl_b32 s3, s8, 2
	s_add_u32 s3, s16, s3
	v_writelane_b32 v232, s5, 8
	s_addc_u32 s4, s17, 0
	s_add_u32 s14, s3, 0xbb40000
	s_addc_u32 s15, s4, 0
	s_add_u32 s3, s16, s9
	s_addc_u32 s4, s17, 0
	v_writelane_b32 v232, s8, 9
	s_add_u32 s8, s3, 0x13b50000
	v_writelane_b32 v232, s9, 10
	s_addc_u32 s9, s4, 0
	s_mul_i32 s3, s60, 0x1800000
	v_writelane_b32 v232, s60, 11
	s_add_u32 s20, s8, s3
	v_writelane_b32 v232, s8, 12
	s_addc_u32 s21, s9, 0
	s_ashr_i32 s12, s2, 3
	s_ashr_i32 s96, s67, 3
	s_cmpk_lt_i32 s12, 0x160
	v_writelane_b32 v232, s9, 13
	v_mov_b32_e32 v9, v158
	s_cselect_b64 s[4:5], -1, 0
	v_writelane_b32 v232, s4, 14
	v_readfirstlane_b32 s3, v9
	s_cmpk_gt_i32 s12, 0x15f
	v_writelane_b32 v232, s5, 15
	s_cbranch_scc1 .LBB0_208
	v_lshlrev_b32_e32 v0, 4, v9
	v_add_u32_e32 v1, 0x2000, v0
	v_ashrrev_i32_e32 v2, 31, v1
	v_lshrrev_b32_e32 v2, 22, v2
	v_add_u32_e32 v2, v1, v2
	v_ashrrev_i32_e32 v8, 10, v2
	v_mul_i32_i24_e32 v2, 0x400, v8
	v_sub_u32_e32 v1, v1, v2
	v_lshrrev_b32_e32 v2, 4, v1
	v_bitop3_b32 v1, v2, v1, 32 bitop3:0x6c
	v_ashrrev_i32_e32 v2, 31, v1
	v_lshrrev_b32_e32 v2, 26, v2
	v_add_u32_e32 v2, v1, v2
	v_lshlrev_b32_e32 v3, 3, v8
	v_ashrrev_i32_e32 v10, 6, v2
	v_and_b32_e32 v3, -16, v3
	v_add_u32_e32 v3, v10, v3
	v_and_b32_e32 v4, 3, v10
	s_mov_b32 s4, 0xfffe0
	v_lshrrev_b32_e32 v5, 2, v3
	v_lshlrev_b32_e32 v6, 1, v3
	v_and_b32_e32 v2, 0xc0, v2
	v_and_or_b32 v4, v3, s4, v4
	v_and_b32_e32 v5, 4, v5
	v_and_b32_e32 v6, 24, v6
	v_sub_u32_e32 v1, v1, v2
	v_mov_b32_e32 v2, 1
	v_or3_b32 v4, v4, v5, v6
	v_lshlrev_b32_e32 v5, 5, v8
	v_ashrrev_i16_sdwa v1, v2, sext(v1) dst_sel:DWORD dst_unused:UNUSED_PAD src0_sel:DWORD src1_sel:BYTE_0
	v_and_b32_e32 v5, 32, v5
	v_bfe_i32 v11, v1, 0, 16
	v_add_lshl_u32 v1, v5, v11, 1
	v_lshl_add_u32 v128, v4, 12, v1
	v_lshl_add_u32 v130, v3, 12, v1
	v_bfe_i32 v1, v9, 27, 1
	v_lshrrev_b32_e32 v1, 22, v1
	v_add_u32_e32 v1, v0, v1
	v_and_b32_e32 v1, 0xfffffc00, v1
	v_sub_u32_e32 v0, v0, v1
	v_lshrrev_b32_e32 v1, 4, v0
	v_bitop3_b32 v1, v1, v0, 32 bitop3:0x6c
	v_ashrrev_i32_e32 v0, 31, v0
	v_lshrrev_b32_e32 v0, 26, v0
	v_add_u32_e32 v0, v1, v0
	v_ashrrev_i32_e32 v12, 6, v0
	v_ashrrev_i32_e32 v0, 31, v9
	v_lshrrev_b32_e32 v0, 26, v0
	v_add_u32_e32 v0, v9, v0
	v_ashrrev_i32_e32 v13, 6, v0
	v_lshlrev_b32_e32 v0, 3, v13
	v_and_b32_e32 v0, -16, v0
	v_add_u32_e32 v0, v12, v0
	v_and_b32_e32 v3, 3, v12
	s_mul_hi_i32 s9, s12, 0x2e8ba2e9
	v_and_or_b32 v3, v0, s4, v3
	s_lshr_b32 s4, s9, 31
	s_ashr_i32 s9, s9, 6
	s_add_i32 s4, s9, s4
	s_lshl_b32 s9, s4, 3
	s_mulk_i32 s4, 0x160
	s_sub_i32 s11, s12, s4
	s_bfe_u32 s4, s11, 0x3001c
	s_add_i32 s13, s11, s4
	s_sext_i32_i16 s4, s13
	s_and_b32 s13, s13, 0xfff8
	v_lshrrev_b32_e32 v4, 2, v0
	v_lshlrev_b32_e32 v5, 1, v0
	s_sub_i32 s11, s11, s13
	v_and_b32_e32 v4, 4, v4
	v_and_b32_e32 v5, 24, v5
	s_sext_i32_i16 s11, s11
	s_ashr_i32 s5, s3, 8
	v_or3_b32 v3, v3, v4, v5
	v_mul_i32_i24_e32 v5, 64, v12
	s_lshr_b32 s4, s4, 3
	s_add_i32 s40, s9, s11
	s_ashr_i32 s8, s3, 6
	v_sub_u32_e32 v1, v1, v5
	s_ashr_i32 s41, s40, 31
	s_bfe_i64 s[24:25], s[4:5], 0x100000
	s_lshl_b32 s10, s8, 10
	v_lshlrev_b32_e32 v4, 5, v13
	v_ashrrev_i16_sdwa v1, v2, sext(v1) dst_sel:DWORD dst_unused:UNUSED_PAD src0_sel:DWORD src1_sel:BYTE_0
	s_lshl_b64 s[22:23], s[40:41], 20
	s_lshl_b64 s[24:25], s[24:25], 20
	v_and_b32_e32 v4, 32, v4
	v_bfe_i32 v14, v1, 0, 16
	s_add_u32 s44, s16, s24
	v_add_lshl_u32 v1, v4, v14, 1
	s_addc_u32 s45, s17, s25
	s_add_i32 s11, s10, 0
	v_lshl_add_u32 v132, v3, 12, v1
	s_add_i32 m0, s11, 0x10000
	v_lshl_add_u32 v134, v0, 12, v1
	global_load_lds_dwordx4 v132, s[44:45]
	s_add_i32 m0, s11, 0x12000
	s_add_u32 s42, s97, s22
	global_load_lds_dwordx4 v128, s[44:45]
	s_addc_u32 s43, s94, s23
	s_mov_b32 m0, s11
	s_add_i32 s13, s11, 0x2000
	global_load_lds_dwordx4 v134, s[42:43]
	s_mov_b32 m0, s13
	s_add_u32 s22, s44, 0x80000
	global_load_lds_dwordx4 v130, s[42:43]
	s_addc_u32 s23, s45, 0
	s_add_i32 m0, s11, 0x14000
	v_mov_b32_e32 v133, 0
	global_load_lds_dwordx4 v132, s[22:23]
	s_add_i32 m0, s11, 0x16000
	v_mov_b32_e32 v129, v133
	global_load_lds_dwordx4 v128, s[22:23]
	s_add_u32 s22, s42, 0x80000
	s_addc_u32 s23, s43, 0
	s_add_i32 s30, s11, 0x4000
	s_mov_b32 m0, s30
	s_add_i32 s31, s11, 0x6000
	global_load_lds_dwordx4 v134, s[22:23]
	s_mov_b32 m0, s31
	v_mov_b32_e32 v135, v133
	global_load_lds_dwordx4 v130, s[22:23]
	v_mov_b32_e32 v131, v133
	s_mov_b32 s33, 0
	v_lshl_add_u64 v[6:7], s[44:45], 0, v[132:133]
	v_lshl_add_u64 v[4:5], s[44:45], 0, v[128:129]
	v_lshl_add_u64 v[2:3], s[42:43], 0, v[134:135]
	s_cmp_lg_u32 s5, 1
	v_lshl_add_u64 v[0:1], s[42:43], 0, v[130:131]
	s_setprio 1
	s_cbranch_scc1 .LBB0_199
	s_barrier
	s_setprio 0

; __device__ __forceinline__ int fresh_tid() { int t = threadIdx.x; asm volatile("" : "+v"(t)); return t; }
; #define PG8_STAGE(bufoff, gbase, voff) do { _Pragma("unroll") for (int _i = 0; _i < 2; ++_i) \
;         __builtin_amdgcn_global_load_lds((const unsigned*)((const char*)(gbase) + (voff)[_i]), (LAS unsigned*)(lds + (bufoff) + ldsw + _i * 8192), 16, 0, 0); } while (0)
; #define PG8_WAIT_V(n) asm volatile("s_waitcnt vmcnt(" #n ")" ::: "memory")
; #define PG8_BAR __builtin_amdgcn_s_barrier()
; template <class Epi>
; __device__ __forceinline__ void gemm_phase(LAS unsigned char* lds, const Gemm g, const StaticOrder& S, const Epi& E) {
;     const int tid = fresh_tid(), wid = __builtin_amdgcn_readfirstlane(tid >> 6), lane = tid & 63, wr = wid >> 2, wc = wid & 3, fr = lane & 15, fq = lane >> 4;
;     const int K = g.K, nt = K / BK;
;     unsigned voffA[2], voffB[2];
; #pragma unroll
;     for (int i = 0; i < 2; ++i) { int R, C; stage_rc(tid * 16 + i * 8192, R, C); const int Rb = (R & ~31) + perm32(R & 31);
;         voffA[i] = (unsigned)(R * K + C) * 2u; voffB[i] = (unsigned)(Rb * K + C) * 2u; }
;     const size_t kstep = (size_t)(BK * 2);
;     const size_t hstep = (size_t)HALF * K * 2;
;     const size_t tstep = 2 * hstep;
;     const unsigned ldsw = (unsigned)wid * 1024u;
;     const int aoff = lds_byte(wr * 64 + fr, fq * 8), boff = lds_byte(wc * 32 + fr, fq * 8);
;     ...
;     Unit cur, nxt; int ui = 0;
;     if (!S.next(0, cur)) return;
;     f32x4 acc[2][2][4][2];
; #pragma unroll
;     for (int a = 0; a < 2; ++a)
; #pragma unroll
;         for (int b = 0; b < 2; ++b)
; #pragma unroll
;             for (int m = 0; m < 4; ++m)
; #pragma unroll
;                 for (int n = 0; n < 2; ++n) acc[a][b][m][n] = (f32x4){0.f, 0.f, 0.f, 0.f};
;     bf16x8 At[4][2], B0[2][2], B1[2][2];
;     const char* cA = (const char*)g.A + (size_t)cur.pm * tstep; const char* cB = (const char*)g.Bt + (size_t)cur.pn * tstep;
;     PG8_STAGE(PG8_SB(0, 0), cB, voffB); PG8_STAGE(PG8_SA(0, 0), cA, voffA); PG8_STAGE(PG8_SB(0, 1), cB + hstep, voffB); PG8_STAGE(PG8_SA(0, 1), cA + hstep, voffA);
;     if (wr == 1) PG8_BAR;
;     PG8_WAIT_V(4); PG8_BAR;
.LBB0_272:
	s_or_b64 exec, exec, s[4:5]
	s_add_u32 s4, s16, 0xfb50000
	s_addc_u32 s5, s17, 0
	s_lshl_b32 s3, s3, 1
	s_add_u32 s24, s4, s3
	v_writelane_b32 v232, s4, 16
	s_addc_u32 s25, s5, 0
	s_cmp_lt_i32 s12, 64
	v_writelane_b32 v232, s5, 17
	s_cselect_b64 s[4:5], -1, 0
	v_writelane_b32 v232, s4, 18
	v_mov_b32_e32 v8, v158
	s_waitcnt lgkmcnt(0)
	v_writelane_b32 v232, s5, 19
	s_barrier
	s_cmp_gt_i32 s12, 63
	v_readfirstlane_b32 s3, v8
	v_writelane_b32 v232, s62, 20
	v_writelane_b32 v232, s61, 21
	s_cbranch_scc1 .LBB0_288
	v_lshlrev_b32_e32 v0, 4, v8
	v_add_u32_e32 v1, 0x2000, v0
	v_ashrrev_i32_e32 v2, 31, v1
	v_lshrrev_b32_e32 v2, 22, v2
	v_add_u32_e32 v2, v1, v2
	v_ashrrev_i32_e32 v9, 10, v2
	v_mul_i32_i24_e32 v2, 0x400, v9
	v_sub_u32_e32 v1, v1, v2
	v_lshrrev_b32_e32 v2, 4, v1
	v_bitop3_b32 v1, v2, v1, 32 bitop3:0x6c
	v_ashrrev_i32_e32 v2, 31, v1
	v_lshrrev_b32_e32 v2, 26, v2
	v_add_u32_e32 v2, v1, v2
	v_lshlrev_b32_e32 v3, 3, v9
	v_ashrrev_i32_e32 v10, 6, v2
	v_and_b32_e32 v3, -16, v3
	v_add_u32_e32 v3, v10, v3
	v_and_b32_e32 v4, 3, v10
	s_mov_b32 s7, 0x7fffe0
	v_lshrrev_b32_e32 v5, 2, v3
	v_lshlrev_b32_e32 v6, 1, v3
	v_and_b32_e32 v2, 0xc0, v2
	v_and_or_b32 v4, v3, s7, v4
	v_and_b32_e32 v5, 4, v5
	v_and_b32_e32 v6, 24, v6
	v_sub_u32_e32 v1, v1, v2
	v_mov_b32_e32 v2, 1
	v_or3_b32 v4, v4, v5, v6
	v_lshlrev_b32_e32 v5, 5, v9
	v_ashrrev_i16_sdwa v1, v2, sext(v1) dst_sel:DWORD dst_unused:UNUSED_PAD src0_sel:DWORD src1_sel:BYTE_0
	s_movk_i32 s4, 0x1600
	v_and_b32_e32 v11, 32, v5
	v_bfe_i32 v12, v1, 0, 16
	v_mul_u32_u24_e32 v4, 0x1600, v4
	v_add_u32_e32 v1, v11, v12
	v_mul_lo_u32 v3, v3, s4
	v_add_lshl_u32 v128, v4, v1, 1
	v_add_lshl_u32 v130, v1, v3, 1
	v_bfe_i32 v1, v8, 27, 1
	v_lshrrev_b32_e32 v1, 22, v1
	v_add_u32_e32 v1, v0, v1
	v_and_b32_e32 v1, 0xfffffc00, v1
	v_sub_u32_e32 v0, v0, v1
	v_lshrrev_b32_e32 v1, 4, v0
	v_bitop3_b32 v1, v1, v0, 32 bitop3:0x6c
	v_ashrrev_i32_e32 v0, 31, v0
	v_lshrrev_b32_e32 v0, 26, v0
	v_add_u32_e32 v0, v1, v0
	v_ashrrev_i32_e32 v13, 6, v0
	v_ashrrev_i32_e32 v0, 31, v8
	v_lshrrev_b32_e32 v0, 26, v0
	v_add_u32_e32 v0, v8, v0
	v_ashrrev_i32_e32 v14, 6, v0
	v_lshlrev_b32_e32 v0, 3, v14
	s_add_u32 s10, s16, 0x2c00000
	v_and_b32_e32 v0, -16, v0
	s_addc_u32 s11, s17, 0
	v_add_u32_e32 v0, v13, v0
	v_and_b32_e32 v3, 3, v13
	s_ashr_i32 s22, s12, 31
	v_and_or_b32 v3, v0, s7, v3
	s_lshr_b32 s7, s22, 26
	s_add_i32 s7, s12, s7
	s_ashr_i32 s8, s7, 6
	s_and_b32 s7, s7, 0xffc0
	s_sub_i32 s7, s12, s7
	s_lshl_b32 s9, s8, 3
	s_bfe_i32 s8, s7, 0x80000
	v_lshrrev_b32_e32 v4, 2, v0
	v_lshlrev_b32_e32 v5, 1, v0
	s_bfe_u32 s8, s8, 0x3000c
	v_and_b32_e32 v4, 4, v4
	v_and_b32_e32 v5, 24, v5
	s_add_i32 s23, s7, s8
	v_or3_b32 v3, v3, v4, v5
	v_lshlrev_b32_e32 v4, 5, v14
	s_bfe_i32 s8, s23, 0x80000
	s_and_b32 s23, s23, 0xf8
	v_and_b32_e32 v15, 32, v4
	v_mul_i32_i24_e32 v4, 64, v13
	s_sext_i32_i16 s26, s8
	s_sub_i32 s7, s7, s23
	s_ashr_i32 s6, s3, 6
	v_sub_u32_e32 v1, v1, v4
	s_sext_i32_i8 s7, s7
	s_ashr_i32 s23, s26, 3
	s_ashr_i32 s5, s3, 8
	s_lshl_b32 s13, s6, 10
	v_ashrrev_i16_sdwa v1, v2, sext(v1) dst_sel:DWORD dst_unused:UNUSED_PAD src0_sel:DWORD src1_sel:BYTE_0
	s_lshr_b32 s8, s26, 3
	s_add_i32 s61, s9, s7
	s_mul_hi_i32 s26, s23, 0x2c0000
	s_mul_i32 s23, s23, 0x2c0000
	v_bfe_i32 v16, v1, 0, 16
	s_add_u32 s50, s10, s23
	v_mul_u32_u24_e32 v3, 0x1600, v3
	v_add_u32_e32 v1, v15, v16
	s_addc_u32 s51, s11, s26
	s_add_i32 s23, s13, 0
	v_add_lshl_u32 v132, v3, v1, 1
	s_add_i32 m0, s23, 0x10000
	s_mul_i32 s9, s61, 0x2c0000
	global_load_lds_dwordx4 v132, s[50:51]
	s_add_i32 m0, s23, 0x12000
	v_mul_lo_u32 v0, v0, s4
	s_mul_hi_i32 s7, s61, 0x2c0000
	s_add_u32 s48, s20, s9
	v_add_lshl_u32 v134, v1, v0, 1
	global_load_lds_dwordx4 v128, s[50:51]
	s_addc_u32 s49, s21, s7
	s_mov_b32 m0, s23
	s_add_i32 s30, s23, 0x2000
	global_load_lds_dwordx4 v134, s[48:49]
	s_mov_b32 m0, s30
	s_add_u32 s26, s50, 0x160000
	global_load_lds_dwordx4 v130, s[48:49]
	s_addc_u32 s27, s51, 0
	s_add_i32 m0, s23, 0x14000
	v_mov_b32_e32 v133, 0
	global_load_lds_dwordx4 v132, s[26:27]
	s_add_i32 m0, s23, 0x16000
	v_mov_b32_e32 v129, v133
	global_load_lds_dwordx4 v128, s[26:27]
	s_add_u32 s26, s48, 0x160000
	s_addc_u32 s27, s49, 0
	s_add_i32 s31, s23, 0x4000
	s_mov_b32 m0, s31
	s_add_i32 s33, s23, 0x6000
	global_load_lds_dwordx4 v134, s[26:27]
	s_mov_b32 m0, s33
	v_mov_b32_e32 v135, v133
	global_load_lds_dwordx4 v130, s[26:27]
	v_mov_b32_e32 v131, v133
	v_lshl_add_u64 v[6:7], s[50:51], 0, v[132:133]
	v_lshl_add_u64 v[4:5], s[50:51], 0, v[128:129]
	v_lshl_add_u64 v[2:3], s[48:49], 0, v[134:135]
	v_lshl_add_u64 v[0:1], s[48:49], 0, v[130:131]
	s_cmp_lg_u32 s5, 1
	s_mov_b32 s9, 0x16000
	s_setprio 1
	s_cbranch_scc1 .LBB0_275
	s_barrier
	s_setprio 0

; __device__ __forceinline__ int fresh_tid() { int t = threadIdx.x; asm volatile("" : "+v"(t)); return t; }
; #define PG8_STAGE(bufoff, gbase, voff) do { _Pragma("unroll") for (int _i = 0; _i < 2; ++_i) \
;         __builtin_amdgcn_global_load_lds((const unsigned*)((const char*)(gbase) + (voff)[_i]), (LAS unsigned*)(lds + (bufoff) + ldsw + _i * 8192), 16, 0, 0); } while (0)
; #define PG8_WAIT_V(n) asm volatile("s_waitcnt vmcnt(" #n ")" ::: "memory")
; #define PG8_BAR __builtin_amdgcn_s_barrier()
; template <class Epi>
; __device__ __forceinline__ void gemm_phase(LAS unsigned char* lds, const Gemm g, const StaticOrder& S, const Epi& E) {
;     const int tid = fresh_tid(), wid = __builtin_amdgcn_readfirstlane(tid >> 6), lane = tid & 63, wr = wid >> 2, wc = wid & 3, fr = lane & 15, fq = lane >> 4;
;     const int K = g.K, nt = K / BK;
;     unsigned voffA[2], voffB[2];
; #pragma unroll
;     for (int i = 0; i < 2; ++i) { int R, C; stage_rc(tid * 16 + i * 8192, R, C); const int Rb = (R & ~31) + perm32(R & 31);
;         voffA[i] = (unsigned)(R * K + C) * 2u; voffB[i] = (unsigned)(Rb * K + C) * 2u; }
;     const size_t kstep = (size_t)(BK * 2);
;     const size_t hstep = (size_t)HALF * K * 2;
;     const size_t tstep = 2 * hstep;
;     const unsigned ldsw = (unsigned)wid * 1024u;
;     const int aoff = lds_byte(wr * 64 + fr, fq * 8), boff = lds_byte(wc * 32 + fr, fq * 8);
;     ...
;     Unit cur, nxt; int ui = 0;
;     if (!S.next(0, cur)) return;
;     f32x4 acc[2][2][4][2];
; #pragma unroll
;     for (int a = 0; a < 2; ++a)
; #pragma unroll
;         for (int b = 0; b < 2; ++b)
; #pragma unroll
;             for (int m = 0; m < 4; ++m)
; #pragma unroll
;                 for (int n = 0; n < 2; ++n) acc[a][b][m][n] = (f32x4){0.f, 0.f, 0.f, 0.f};
;     bf16x8 At[4][2], B0[2][2], B1[2][2];
;     const char* cA = (const char*)g.A + (size_t)cur.pm * tstep; const char* cB = (const char*)g.Bt + (size_t)cur.pn * tstep;
;     PG8_STAGE(PG8_SB(0, 0), cB, voffB); PG8_STAGE(PG8_SA(0, 0), cA, voffA); PG8_STAGE(PG8_SB(0, 1), cB + hstep, voffB); PG8_STAGE(PG8_SA(0, 1), cA + hstep, voffA);
;     if (wr == 1) PG8_BAR;
;     PG8_WAIT_V(4); PG8_BAR;
.LBB0_399:
	s_or_b64 exec, exec, s[2:3]
	v_mov_b32_e32 v10, v158
	s_waitcnt lgkmcnt(0)
	s_barrier
	s_cmpk_gt_i32 s12, 0xbf
	v_readfirstlane_b32 s10, v10
	s_cbranch_scc1 .LBB0_415
	v_lshlrev_b32_e32 v0, 4, v10
	v_add_u32_e32 v1, 0x2000, v0
	v_ashrrev_i32_e32 v2, 31, v1
	v_lshrrev_b32_e32 v2, 22, v2
	v_add_u32_e32 v2, v1, v2
	v_ashrrev_i32_e32 v8, 10, v2
	v_mul_i32_i24_e32 v2, 0x400, v8
	v_sub_u32_e32 v1, v1, v2
	v_lshrrev_b32_e32 v2, 4, v1
	v_bitop3_b32 v1, v2, v1, 32 bitop3:0x6c
	v_ashrrev_i32_e32 v2, 31, v1
	v_lshrrev_b32_e32 v2, 26, v2
	v_add_u32_e32 v2, v1, v2
	v_lshlrev_b32_e32 v3, 3, v8
	v_ashrrev_i32_e32 v9, 6, v2
	v_and_b32_e32 v3, -16, v3
	v_add_u32_e32 v3, v9, v3
	v_and_b32_e32 v4, 3, v9
	s_mov_b32 s2, 0xfffe0
	v_lshrrev_b32_e32 v5, 2, v3
	v_lshlrev_b32_e32 v6, 1, v3
	v_and_b32_e32 v2, 0xc0, v2
	v_and_or_b32 v4, v3, s2, v4
	v_and_b32_e32 v5, 4, v5
	v_and_b32_e32 v6, 24, v6
	v_sub_u32_e32 v1, v1, v2
	v_mov_b32_e32 v2, 1
	v_or3_b32 v4, v4, v5, v6
	v_lshlrev_b32_e32 v5, 5, v8
	v_ashrrev_i16_sdwa v1, v2, sext(v1) dst_sel:DWORD dst_unused:UNUSED_PAD src0_sel:DWORD src1_sel:BYTE_0
	v_and_b32_e32 v5, 32, v5
	v_bfe_i32 v11, v1, 0, 16
	v_add_lshl_u32 v1, v5, v11, 1
	v_lshl_add_u32 v128, v4, 12, v1
	v_lshl_add_u32 v130, v3, 12, v1
	v_bfe_i32 v1, v10, 27, 1
	v_lshrrev_b32_e32 v1, 22, v1
	v_add_u32_e32 v1, v0, v1
	v_and_b32_e32 v1, 0xfffffc00, v1
	v_sub_u32_e32 v0, v0, v1
	v_lshrrev_b32_e32 v1, 4, v0
	v_bitop3_b32 v1, v1, v0, 32 bitop3:0x6c
	v_ashrrev_i32_e32 v0, 31, v0
	v_lshrrev_b32_e32 v0, 26, v0
	v_add_u32_e32 v0, v1, v0
	v_ashrrev_i32_e32 v12, 6, v0
	v_ashrrev_i32_e32 v0, 31, v10
	v_lshrrev_b32_e32 v0, 26, v0
	v_add_u32_e32 v0, v10, v0
	v_ashrrev_i32_e32 v13, 6, v0
	v_lshlrev_b32_e32 v0, 3, v13
	v_and_b32_e32 v0, -16, v0
	v_add_u32_e32 v0, v12, v0
	v_and_b32_e32 v3, 3, v12
	s_add_u32 s11, s16, 0x8400000
	v_and_or_b32 v3, v0, s2, v3
	s_mul_hi_i32 s2, s12, 0x2aaaaaab
	s_addc_u32 s22, s17, 0
	s_lshr_b32 s3, s2, 31
	s_ashr_i32 s2, s2, 5
	s_add_i32 s2, s2, s3
	s_lshl_b32 s3, s2, 3
	s_mulk_i32 s2, 0xc0
	s_sub_i32 s2, s12, s2
	s_bfe_u32 s4, s2, 0x3001c
	s_add_i32 s7, s2, s4
	s_sext_i32_i16 s4, s7
	s_and_b32 s7, s7, 0xfff8
	v_lshrrev_b32_e32 v4, 2, v0
	v_lshlrev_b32_e32 v5, 1, v0
	s_sub_i32 s2, s2, s7
	v_and_b32_e32 v4, 4, v4
	v_and_b32_e32 v5, 24, v5
	s_sext_i32_i16 s2, s2
	s_ashr_i32 s5, s10, 6
	v_or3_b32 v3, v3, v4, v5
	v_mul_i32_i24_e32 v5, 64, v12
	s_lshr_b32 s4, s4, 3
	s_add_i32 s44, s3, s2
	v_sub_u32_e32 v1, v1, v5
	s_ashr_i32 s45, s44, 31
	s_bfe_i64 s[8:9], s[4:5], 0x100000
	s_ashr_i32 s6, s10, 8
	s_lshl_b32 s23, s5, 10
	v_lshlrev_b32_e32 v4, 5, v13
	v_ashrrev_i16_sdwa v1, v2, sext(v1) dst_sel:DWORD dst_unused:UNUSED_PAD src0_sel:DWORD src1_sel:BYTE_0
	s_lshl_b64 s[2:3], s[44:45], 20
	s_lshl_b64 s[8:9], s[8:9], 20
	v_and_b32_e32 v4, 32, v4
	v_bfe_i32 v14, v1, 0, 16
	s_add_u32 s48, s11, s8
	v_add_lshl_u32 v1, v4, v14, 1
	s_addc_u32 s49, s22, s9
	s_add_i32 s27, s23, 0
	v_lshl_add_u32 v132, v3, 12, v1
	s_add_i32 m0, s27, 0x10000
	v_lshl_add_u32 v134, v0, 12, v1
	global_load_lds_dwordx4 v132, s[48:49]
	s_add_i32 m0, s27, 0x12000
	s_add_u32 s46, s97, s2
	global_load_lds_dwordx4 v128, s[48:49]
	s_addc_u32 s47, s94, s3
	s_mov_b32 m0, s27
	s_add_i32 s30, s27, 0x2000
	global_load_lds_dwordx4 v134, s[46:47]
	s_mov_b32 m0, s30
	s_add_u32 s2, s48, 0x80000
	global_load_lds_dwordx4 v130, s[46:47]
	s_addc_u32 s3, s49, 0
	s_add_i32 m0, s27, 0x14000
	v_mov_b32_e32 v137, 0
	global_load_lds_dwordx4 v132, s[2:3]
	s_add_i32 m0, s27, 0x16000
	v_mov_b32_e32 v133, v137
	global_load_lds_dwordx4 v128, s[2:3]
	s_add_u32 s2, s46, 0x80000
	s_addc_u32 s3, s47, 0
	s_add_i32 s31, s27, 0x4000
	s_mov_b32 m0, s31
	s_add_i32 s33, s27, 0x6000
	global_load_lds_dwordx4 v134, s[2:3]
	s_mov_b32 m0, s33
	v_mov_b32_e32 v129, v137
	global_load_lds_dwordx4 v130, s[2:3]
	v_mov_b32_e32 v135, v137
	v_mov_b32_e32 v131, v137
	s_mov_b32 s36, 0
	v_lshl_add_u64 v[6:7], s[48:49], 0, v[132:133]
	v_lshl_add_u64 v[4:5], s[48:49], 0, v[128:129]
	v_lshl_add_u64 v[2:3], s[46:47], 0, v[134:135]
	s_cmp_lg_u32 s6, 1
	v_lshl_add_u64 v[0:1], s[46:47], 0, v[130:131]
	s_setprio 1
	s_cbranch_scc1 .LBB0_402
	s_barrier
	s_setprio 0

; #define LAS __attribute__((address_space(3)))
; __device__ __forceinline__ int fresh_tid() { int t = threadIdx.x; asm volatile("" : "+v"(t)); return t; }
; __device__ __forceinline__ int v_rd_base(int lane) { return ((lane & 3) << 3) | (((lane >> 2) & 3) << 6) | (((lane >> 4) & 1) << 5) | (((lane >> 5) & 1) << 8); }
; __device__ __forceinline__ void attn_phase(unsigned char* ws_, unsigned char* outb, const float* rpb, LAS unsigned char* lds, int wg, int nwg, int grp) {
;     const int tid = fresh_tid(), wid = __builtin_amdgcn_readfirstlane(tid >> 6), lane = tid & 63, r32 = lane & 31, hi = lane >> 5;
;     const bf16_t* qkv = (const bf16_t*)(ws_ + OFF_X + (size_t)grp * XG_BYTES);
;     LAS unsigned char* V_lds = lds; LAS unsigned char* K_lds = lds + 32768;
;     LAS float* wsf = (LAS float*)(lds + 65536) + wid * 64; LAS float* li_l = wsf; LAS float* al_l = wsf + 32;
;     LAS unsigned char* oL = lds + 69888 + wid * 8192;
;     LAS unsigned char* qL = oL + lane * 16;
;     LAS float* rpbL = (LAS float*)(lds + 65536 + 2048);
;     const int krow = tid >> 4, kcs = ((tid & 15) ^ (krow & 7)) * 8;
;     int vk0, vk1, vc0, vc1;
;     { const int D0 = tid * 16, D1 = D0 + 8192;
;       const int st0 = D0 >> 9, kk0 = (st0 >> 2) * 8 + ((D0 & 511) >> 6); vk0 = (kk0 & ~0xC) | ((kk0 & 4) << 1) | ((kk0 & 8) >> 1); vc0 = (st0 & 3) * 32 + ((D0 & 63) >> 4) * 8;
;       const int st1 = D1 >> 9, kk1 = (st1 >> 2) * 8 + ((D1 & 511) >> 6); vk1 = (kk1 & ~0xC) | ((kk1 & 4) << 1) | ((kk1 & 8) >> 1); vc1 = (st1 & 3) * 32 + ((D1 & 63) >> 4) * 8; }
;     const unsigned dmaw = (unsigned)wid * 1024u;
;     const int vrd = v_rd_base(lane);
;     const int qb = wid >> 1, half = wid & 1, iq = 32 * half + r32;
;     int vw = wg;
;     int gj = -1;
;     if (vw >= 128) return;
.LBB0_467:
	s_or_b64 exec, exec, s[2:3]
	s_waitcnt lgkmcnt(0)
	s_barrier
	s_load_dwordx2 s[2:3], s[0:1], 0xb0
	v_mov_b32_e32 v160, v158
	s_cmpk_gt_i32 s35, 0x7f
	s_waitcnt lgkmcnt(0)
	v_writelane_b32 v232, s2, 24
	s_nop 1
	v_writelane_b32 v232, s3, 25
	v_readfirstlane_b32 s2, v160
	s_cbranch_scc1 .LBB0_555
	s_cmp_gt_u32 s2, 0xff
	s_cbranch_scc1 .Latt_prio_skip
	s_setprio 1

; __device__ __forceinline__ int fresh_tid() { int t = threadIdx.x; asm volatile("" : "+v"(t)); return t; }
; #define PG8_STAGE(bufoff, gbase, voff) do { _Pragma("unroll") for (int _i = 0; _i < 2; ++_i) \
;         __builtin_amdgcn_global_load_lds((const unsigned*)((const char*)(gbase) + (voff)[_i]), (LAS unsigned*)(lds + (bufoff) + ldsw + _i * 8192), 16, 0, 0); } while (0)
; #define PG8_WAIT_V(n) asm volatile("s_waitcnt vmcnt(" #n ")" ::: "memory")
; #define PG8_BAR __builtin_amdgcn_s_barrier()
; template <class Epi>
; __device__ __forceinline__ void gemm_phase(LAS unsigned char* lds, const Gemm g, const StaticOrder& S, const Epi& E) {
;     const int tid = fresh_tid(), wid = __builtin_amdgcn_readfirstlane(tid >> 6), lane = tid & 63, wr = wid >> 2, wc = wid & 3, fr = lane & 15, fq = lane >> 4;
;     const int K = g.K, nt = K / BK;
;     unsigned voffA[2], voffB[2];
; #pragma unroll
;     for (int i = 0; i < 2; ++i) { int R, C; stage_rc(tid * 16 + i * 8192, R, C); const int Rb = (R & ~31) + perm32(R & 31);
;         voffA[i] = (unsigned)(R * K + C) * 2u; voffB[i] = (unsigned)(Rb * K + C) * 2u; }
;     const size_t kstep = (size_t)(BK * 2);
;     const size_t hstep = (size_t)HALF * K * 2;
;     const size_t tstep = 2 * hstep;
;     const unsigned ldsw = (unsigned)wid * 1024u;
;     const int aoff = lds_byte(wr * 64 + fr, fq * 8), boff = lds_byte(wc * 32 + fr, fq * 8);
;     ...
;     Unit cur, nxt; int ui = 0;
;     if (!S.next(0, cur)) return;
;     f32x4 acc[2][2][4][2];
; #pragma unroll
;     for (int a = 0; a < 2; ++a)
; #pragma unroll
;         for (int b = 0; b < 2; ++b)
; #pragma unroll
;             for (int m = 0; m < 4; ++m)
; #pragma unroll
;                 for (int n = 0; n < 2; ++n) acc[a][b][m][n] = (f32x4){0.f, 0.f, 0.f, 0.f};
;     bf16x8 At[4][2], B0[2][2], B1[2][2];
;     const char* cA = (const char*)g.A + (size_t)cur.pm * tstep; const char* cB = (const char*)g.Bt + (size_t)cur.pn * tstep;
;     PG8_STAGE(PG8_SB(0, 0), cB, voffB); PG8_STAGE(PG8_SA(0, 0), cA, voffA); PG8_STAGE(PG8_SB(0, 1), cB + hstep, voffB); PG8_STAGE(PG8_SA(0, 1), cA + hstep, voffA);
;     if (wr == 1) PG8_BAR;
;     PG8_WAIT_V(4); PG8_BAR;
;     PG8_STAGE(PG8_SB(1, 0), cB + kstep, voffB); PG8_STAGE(PG8_SA(1, 0), cA + kstep, voffA); PG8_STAGE(PG8_SB(1, 1), cB + hstep + kstep, voffB);
;     PG8_WAIT_V(6); PG8_BAR;
.LBB0_666:
	s_or_b64 exec, exec, s[2:3]
	v_readlane_b32 s2, v232, 18
	v_readlane_b32 s3, v232, 19
	v_mov_b32_e32 v9, v158
	s_waitcnt lgkmcnt(0)
	v_cndmask_b32_e64 v0, 0, 1, s[2:3]
	s_barrier
	v_cmp_ne_u32_e64 s[4:5], 1, v0
	s_andn2_b64 vcc, exec, s[2:3]
	v_readfirstlane_b32 s10, v9
	s_cbranch_vccnz .LBB0_678
	v_lshlrev_b32_e32 v0, 4, v9
	v_add_u32_e32 v1, 0x2000, v0
	v_ashrrev_i32_e32 v2, 31, v1
	v_lshrrev_b32_e32 v2, 22, v2
	v_add_u32_e32 v2, v1, v2
	v_ashrrev_i32_e32 v8, 10, v2
	v_mul_i32_i24_e32 v3, 0x400, v8
	v_sub_u32_e32 v1, v1, v3
	v_lshrrev_b32_e32 v3, 4, v1
	v_bitop3_b32 v1, v3, v1, 32 bitop3:0x6c
	v_ashrrev_i32_e32 v3, 31, v1
	v_lshrrev_b32_e32 v3, 26, v3
	v_add_u32_e32 v3, v1, v3
	v_ashrrev_i32_e32 v10, 6, v3
	v_and_b32_e32 v3, 0xc0, v3
	v_sub_u32_e32 v1, v1, v3
	v_mov_b32_e32 v3, 1
	v_ashrrev_i16_sdwa v1, v3, sext(v1) dst_sel:DWORD dst_unused:UNUSED_PAD src0_sel:DWORD src1_sel:BYTE_0
	v_bfe_i32 v11, v1, 0, 16
	v_lshlrev_b32_e32 v1, 3, v8
	v_and_b32_e32 v1, -16, v1
	v_add_u32_e32 v1, v10, v1
	v_lshlrev_b32_e32 v2, 5, v8
	v_and_b32_e32 v4, 3, v10
	s_mov_b32 s2, 0xfffe0
	v_lshrrev_b32_e32 v5, 2, v1
	v_lshlrev_b32_e32 v6, 1, v1
	v_and_b32_e32 v2, 32, v2
	v_and_or_b32 v4, v1, s2, v4
	v_and_b32_e32 v5, 4, v5
	v_and_b32_e32 v6, 24, v6
	v_or3_b32 v4, v4, v5, v6
	v_add_lshl_u32 v2, v2, v11, 1
	v_lshl_add_u32 v128, v4, 12, v2
	v_lshl_add_u32 v130, v1, 12, v2
	v_bfe_i32 v2, v9, 27, 1
	v_lshrrev_b32_e32 v2, 22, v2
	v_add_u32_e32 v2, v0, v2
	v_and_b32_e32 v2, 0xfffffc00, v2
	v_sub_u32_e32 v0, v0, v2
	v_lshrrev_b32_e32 v2, 4, v0
	v_bitop3_b32 v2, v2, v0, 32 bitop3:0x6c
	v_ashrrev_i32_e32 v0, 31, v0
	v_lshrrev_b32_e32 v0, 26, v0
	v_add_u32_e32 v0, v2, v0
	v_ashrrev_i32_e32 v1, 31, v9
	v_ashrrev_i32_e32 v13, 6, v0
	v_lshrrev_b32_e32 v1, 26, v1
	v_mul_i32_i24_e32 v0, 64, v13
	v_add_u32_e32 v1, v9, v1
	v_sub_u32_e32 v0, v2, v0
	v_ashrrev_i32_e32 v12, 6, v1
	v_ashrrev_i16_sdwa v0, v3, sext(v0) dst_sel:DWORD dst_unused:UNUSED_PAD src0_sel:DWORD src1_sel:BYTE_0
	v_bfe_i32 v14, v0, 0, 16
	v_lshlrev_b32_e32 v0, 3, v12
	s_add_u32 s11, s16, 0x9c00000
	v_and_b32_e32 v0, -16, v0
	s_addc_u32 s22, s17, 0
	v_add_u32_e32 v0, v13, v0
	v_and_b32_e32 v2, 3, v13
	s_ashr_i32 s27, s12, 31
	v_and_or_b32 v2, v0, s2, v2
	s_lshr_b32 s2, s27, 26
	s_add_i32 s2, s12, s2
	s_ashr_i32 s3, s2, 6
	s_and_b32 s2, s2, 0xffc0
	s_sub_i32 s2, s12, s2
	s_bfe_i32 s7, s2, 0x80000
	s_bfe_u32 s7, s7, 0x3000c
	s_add_i32 s7, s2, s7
	s_bfe_i32 s8, s7, 0x80000
	s_and_b32 s7, s7, 0xf8
	s_sub_i32 s2, s2, s7
	s_lshl_b32 s3, s3, 3
	s_sext_i32_i16 s8, s8
	s_sext_i32_i8 s2, s2
	s_ashr_i32 s9, s10, 8
	s_lshr_b32 s8, s8, 3
	s_add_i32 s48, s3, s2
	s_ashr_i32 s6, s10, 6
	s_ashr_i32 s49, s48, 31
	s_bfe_i64 s[28:29], s[8:9], 0x100000
	s_lshl_b32 s23, s6, 10
	v_lshlrev_b32_e32 v1, 5, v12
	v_lshrrev_b32_e32 v3, 2, v0
	v_lshlrev_b32_e32 v4, 1, v0
	s_lshl_b64 s[2:3], s[48:49], 20
	s_lshl_b64 s[28:29], s[28:29], 20
	v_and_b32_e32 v1, 32, v1
	v_and_b32_e32 v3, 4, v3
	v_and_b32_e32 v4, 24, v4
	s_add_u32 s52, s11, s28
	v_or3_b32 v2, v2, v3, v4
	v_add_lshl_u32 v1, v1, v14, 1
	s_addc_u32 s53, s22, s29
	s_add_i32 s28, s23, 0
	v_lshl_add_u32 v132, v2, 12, v1
	s_add_i32 m0, s28, 0x10000
	v_lshl_add_u32 v134, v0, 12, v1
	global_load_lds_dwordx4 v132, s[52:53]
	s_add_i32 m0, s28, 0x12000
	s_add_u32 s50, s20, s2
	global_load_lds_dwordx4 v128, s[52:53]
	s_addc_u32 s51, s21, s3
	s_mov_b32 m0, s28
	s_add_i32 s29, s28, 0x2000
	global_load_lds_dwordx4 v134, s[50:51]
	s_mov_b32 m0, s29
	s_add_u32 s2, s52, 0x80000
	global_load_lds_dwordx4 v130, s[50:51]
	s_addc_u32 s3, s53, 0
	s_add_i32 m0, s28, 0x14000
	v_mov_b32_e32 v133, 0
	global_load_lds_dwordx4 v132, s[2:3]
	s_add_i32 m0, s28, 0x16000
	v_mov_b32_e32 v129, v133
	global_load_lds_dwordx4 v128, s[2:3]
	s_add_u32 s2, s50, 0x80000
	s_addc_u32 s3, s51, 0
	s_add_i32 s33, s28, 0x4000
	s_mov_b32 m0, s33
	s_add_i32 s36, s28, 0x6000
	global_load_lds_dwordx4 v134, s[2:3]
	s_mov_b32 m0, s36
	v_mov_b32_e32 v135, v133
	global_load_lds_dwordx4 v130, s[2:3]
	v_mov_b32_e32 v131, v133
	s_mov_b32 s37, 0
	v_lshl_add_u64 v[6:7], s[52:53], 0, v[132:133]
	v_lshl_add_u64 v[4:5], s[52:53], 0, v[128:129]
	v_lshl_add_u64 v[2:3], s[50:51], 0, v[134:135]
	v_lshl_add_u64 v[0:1], s[50:51], 0, v[130:131]
	s_cmp_lg_u32 s9, 1
	s_mov_b64 s[2:3], 0x80000
	s_setprio 1
	s_cbranch_scc1 .LBB0_669
	s_barrier
	s_setprio 0

; __device__ __forceinline__ int fresh_tid() { int t = threadIdx.x; asm volatile("" : "+v"(t)); return t; }
; #define PG8_STAGE(bufoff, gbase, voff) do { _Pragma("unroll") for (int _i = 0; _i < 2; ++_i) \
;         __builtin_amdgcn_global_load_lds((const unsigned*)((const char*)(gbase) + (voff)[_i]), (LAS unsigned*)(lds + (bufoff) + ldsw + _i * 8192), 16, 0, 0); } while (0)
; #define PG8_WAIT_V(n) asm volatile("s_waitcnt vmcnt(" #n ")" ::: "memory")
; #define PG8_BAR __builtin_amdgcn_s_barrier()
; template <class Epi>
; __device__ __forceinline__ void gemm_phase(LAS unsigned char* lds, const Gemm g, const StaticOrder& S, const Epi& E) {
;     const int tid = fresh_tid(), wid = __builtin_amdgcn_readfirstlane(tid >> 6), lane = tid & 63, wr = wid >> 2, wc = wid & 3, fr = lane & 15, fq = lane >> 4;
;     const int K = g.K, nt = K / BK;
;     unsigned voffA[2], voffB[2];
; #pragma unroll
;     for (int i = 0; i < 2; ++i) { int R, C; stage_rc(tid * 16 + i * 8192, R, C); const int Rb = (R & ~31) + perm32(R & 31);
;         voffA[i] = (unsigned)(R * K + C) * 2u; voffB[i] = (unsigned)(Rb * K + C) * 2u; }
;     const size_t kstep = (size_t)(BK * 2);
;     const size_t hstep = (size_t)HALF * K * 2;
;     const size_t tstep = 2 * hstep;
;     const unsigned ldsw = (unsigned)wid * 1024u;
;     const int aoff = lds_byte(wr * 64 + fr, fq * 8), boff = lds_byte(wc * 32 + fr, fq * 8);
;     ...
;     Unit cur, nxt; int ui = 0;
;     if (!S.next(0, cur)) return;
;     f32x4 acc[2][2][4][2];
; #pragma unroll
;     for (int a = 0; a < 2; ++a)
; #pragma unroll
;         for (int b = 0; b < 2; ++b)
; #pragma unroll
;             for (int m = 0; m < 4; ++m)
; #pragma unroll
;                 for (int n = 0; n < 2; ++n) acc[a][b][m][n] = (f32x4){0.f, 0.f, 0.f, 0.f};
;     bf16x8 At[4][2], B0[2][2], B1[2][2];
;     const char* cA = (const char*)g.A + (size_t)cur.pm * tstep; const char* cB = (const char*)g.Bt + (size_t)cur.pn * tstep;
;     PG8_STAGE(PG8_SB(0, 0), cB, voffB); PG8_STAGE(PG8_SA(0, 0), cA, voffA); PG8_STAGE(PG8_SB(0, 1), cB + hstep, voffB); PG8_STAGE(PG8_SA(0, 1), cA + hstep, voffA);
;     if (wr == 1) PG8_BAR;
;     PG8_WAIT_V(4); PG8_BAR;
;     PG8_STAGE(PG8_SB(1, 0), cB + kstep, voffB); PG8_STAGE(PG8_SA(1, 0), cA + kstep, voffA); PG8_STAGE(PG8_SB(1, 1), cB + hstep + kstep, voffB);
;     PG8_WAIT_V(6); PG8_BAR;
.LBB0_789:
	s_or_b64 exec, exec, s[2:3]
	v_readlane_b32 s2, v232, 14
	v_mov_b32_e32 v9, v158
	v_readlane_b32 s3, v232, 15
	s_waitcnt lgkmcnt(0)
	s_barrier
	s_andn2_b64 vcc, exec, s[2:3]
	v_readfirstlane_b32 s10, v9
	s_cbranch_vccnz .LBB0_801
	v_lshlrev_b32_e32 v0, 4, v9
	v_add_u32_e32 v1, 0x2000, v0
	v_ashrrev_i32_e32 v2, 31, v1
	v_lshrrev_b32_e32 v2, 22, v2
	v_add_u32_e32 v2, v1, v2
	v_ashrrev_i32_e32 v8, 10, v2
	v_mul_i32_i24_e32 v2, 0x400, v8
	v_sub_u32_e32 v1, v1, v2
	v_lshrrev_b32_e32 v2, 4, v1
	v_bitop3_b32 v1, v2, v1, 32 bitop3:0x6c
	v_ashrrev_i32_e32 v2, 31, v1
	v_lshrrev_b32_e32 v2, 26, v2
	v_add_u32_e32 v2, v1, v2
	v_lshlrev_b32_e32 v3, 3, v8
	v_ashrrev_i32_e32 v10, 6, v2
	v_and_b32_e32 v3, -16, v3
	v_add_u32_e32 v3, v10, v3
	v_and_b32_e32 v4, 3, v10
	s_mov_b32 s3, 0xfffe0
	v_lshrrev_b32_e32 v5, 2, v3
	v_lshlrev_b32_e32 v6, 1, v3
	v_and_b32_e32 v2, 0xc0, v2
	v_and_or_b32 v4, v3, s3, v4
	v_and_b32_e32 v5, 4, v5
	v_and_b32_e32 v6, 24, v6
	v_sub_u32_e32 v1, v1, v2
	v_mov_b32_e32 v2, 1
	v_or3_b32 v4, v4, v5, v6
	v_lshlrev_b32_e32 v5, 5, v8
	v_ashrrev_i16_sdwa v1, v2, sext(v1) dst_sel:DWORD dst_unused:UNUSED_PAD src0_sel:DWORD src1_sel:BYTE_0
	v_and_b32_e32 v5, 32, v5
	v_bfe_i32 v11, v1, 0, 16
	v_add_lshl_u32 v1, v5, v11, 1
	v_lshl_add_u32 v128, v4, 12, v1
	v_lshl_add_u32 v130, v3, 12, v1
	v_bfe_i32 v1, v9, 27, 1
	v_lshrrev_b32_e32 v1, 22, v1
	v_add_u32_e32 v1, v0, v1
	v_and_b32_e32 v1, 0xfffffc00, v1
	v_sub_u32_e32 v0, v0, v1
	v_lshrrev_b32_e32 v1, 4, v0
	v_bitop3_b32 v1, v1, v0, 32 bitop3:0x6c
	v_ashrrev_i32_e32 v0, 31, v0
	v_lshrrev_b32_e32 v0, 26, v0
	v_add_u32_e32 v0, v1, v0
	v_ashrrev_i32_e32 v12, 6, v0
	v_ashrrev_i32_e32 v0, 31, v9
	v_lshrrev_b32_e32 v0, 26, v0
	v_add_u32_e32 v0, v9, v0
	v_ashrrev_i32_e32 v13, 6, v0
	v_lshlrev_b32_e32 v0, 3, v13
	v_and_b32_e32 v0, -16, v0
	s_add_u32 s11, s16, 0x4200000
	v_add_u32_e32 v0, v12, v0
	v_and_b32_e32 v3, 3, v12
	s_mul_hi_i32 s6, s12, 0x2e8ba2e9
	s_addc_u32 s22, s17, 0
	v_and_or_b32 v3, v0, s3, v3
	s_lshr_b32 s3, s6, 31
	s_ashr_i32 s6, s6, 6
	s_add_i32 s3, s6, s3
	s_lshl_b32 s8, s3, 3
	s_mulk_i32 s3, 0x160
	s_sub_i32 s3, s12, s3
	s_bfe_u32 s6, s3, 0x3001c
	s_add_i32 s9, s3, s6
	s_sext_i32_i16 s6, s9
	s_and_b32 s9, s9, 0xfff8
	v_lshrrev_b32_e32 v4, 2, v0
	v_lshlrev_b32_e32 v5, 1, v0
	s_sub_i32 s3, s3, s9
	v_and_b32_e32 v4, 4, v4
	v_and_b32_e32 v5, 24, v5
	s_sext_i32_i16 s3, s3
	s_ashr_i32 s7, s10, 8
	v_or3_b32 v3, v3, v4, v5
	v_mul_i32_i24_e32 v5, 64, v12
	s_lshr_b32 s6, s6, 3
	s_add_i32 s38, s8, s3
	s_ashr_i32 s2, s10, 6
	v_sub_u32_e32 v1, v1, v5
	s_ashr_i32 s39, s38, 31
	s_bfe_i64 s[28:29], s[6:7], 0x100000
	s_lshl_b32 s23, s2, 10
	v_lshlrev_b32_e32 v4, 5, v13
	v_ashrrev_i16_sdwa v1, v2, sext(v1) dst_sel:DWORD dst_unused:UNUSED_PAD src0_sel:DWORD src1_sel:BYTE_0
	s_lshl_b64 s[8:9], s[38:39], 20
	s_lshl_b64 s[28:29], s[28:29], 20
	v_and_b32_e32 v4, 32, v4
	v_bfe_i32 v14, v1, 0, 16
	s_add_u32 s42, s11, s28
	v_add_lshl_u32 v1, v4, v14, 1
	s_addc_u32 s43, s22, s29
	s_add_i32 s27, s23, 0
	v_lshl_add_u32 v132, v3, 12, v1
	s_add_i32 m0, s27, 0x10000
	v_lshl_add_u32 v134, v0, 12, v1
	global_load_lds_dwordx4 v132, s[42:43]
	s_add_i32 m0, s27, 0x12000
	s_add_u32 s40, s97, s8
	global_load_lds_dwordx4 v128, s[42:43]
	s_addc_u32 s41, s94, s9
	s_mov_b32 m0, s27
	s_add_i32 s28, s27, 0x2000
	global_load_lds_dwordx4 v134, s[40:41]
	s_mov_b32 m0, s28
	s_add_u32 s8, s42, 0x80000
	global_load_lds_dwordx4 v130, s[40:41]
	s_addc_u32 s9, s43, 0
	s_add_i32 m0, s27, 0x14000
	v_mov_b32_e32 v133, 0
	global_load_lds_dwordx4 v132, s[8:9]
	s_add_i32 m0, s27, 0x16000
	v_mov_b32_e32 v129, v133
	global_load_lds_dwordx4 v128, s[8:9]
	s_add_u32 s8, s40, 0x80000
	s_addc_u32 s9, s41, 0
	s_add_i32 s29, s27, 0x4000
	s_mov_b32 m0, s29
	s_add_i32 s33, s27, 0x6000
	global_load_lds_dwordx4 v134, s[8:9]
	s_mov_b32 m0, s33
	v_mov_b32_e32 v135, v133
	global_load_lds_dwordx4 v130, s[8:9]
	v_mov_b32_e32 v131, v133
	s_mov_b32 s39, 0
	v_lshl_add_u64 v[6:7], s[42:43], 0, v[132:133]
	v_lshl_add_u64 v[4:5], s[42:43], 0, v[128:129]
	v_lshl_add_u64 v[2:3], s[40:41], 0, v[134:135]
	s_cmp_lg_u32 s7, 1
	v_lshl_add_u64 v[0:1], s[40:41], 0, v[130:131]
	s_setprio 1
	s_cbranch_scc1 .LBB0_792
	s_barrier
	s_setprio 0

; __device__ __forceinline__ int fresh_tid() { int t = threadIdx.x; asm volatile("" : "+v"(t)); return t; }
; #define PG8_STAGE(bufoff, gbase, voff) do { _Pragma("unroll") for (int _i = 0; _i < 2; ++_i) \
;         __builtin_amdgcn_global_load_lds((const unsigned*)((const char*)(gbase) + (voff)[_i]), (LAS unsigned*)(lds + (bufoff) + ldsw + _i * 8192), 16, 0, 0); } while (0)
; #define PG8_WAIT_V(n) asm volatile("s_waitcnt vmcnt(" #n ")" ::: "memory")
; #define PG8_BAR __builtin_amdgcn_s_barrier()
; template <class Epi>
; __device__ __forceinline__ void gemm_phase(LAS unsigned char* lds, const Gemm g, const StaticOrder& S, const Epi& E) {
;     const int tid = fresh_tid(), wid = __builtin_amdgcn_readfirstlane(tid >> 6), lane = tid & 63, wr = wid >> 2, wc = wid & 3, fr = lane & 15, fq = lane >> 4;
;     const int K = g.K, nt = K / BK;
;     unsigned voffA[2], voffB[2];
; #pragma unroll
;     for (int i = 0; i < 2; ++i) { int R, C; stage_rc(tid * 16 + i * 8192, R, C); const int Rb = (R & ~31) + perm32(R & 31);
;         voffA[i] = (unsigned)(R * K + C) * 2u; voffB[i] = (unsigned)(Rb * K + C) * 2u; }
;     const size_t kstep = (size_t)(BK * 2);
;     const size_t hstep = (size_t)HALF * K * 2;
;     const size_t tstep = 2 * hstep;
;     const unsigned ldsw = (unsigned)wid * 1024u;
;     const int aoff = lds_byte(wr * 64 + fr, fq * 8), boff = lds_byte(wc * 32 + fr, fq * 8);
;     ...
;     Unit cur, nxt; int ui = 0;
;     if (!S.next(0, cur)) return;
;     f32x4 acc[2][2][4][2];
; #pragma unroll
;     for (int a = 0; a < 2; ++a)
; #pragma unroll
;         for (int b = 0; b < 2; ++b)
; #pragma unroll
;             for (int m = 0; m < 4; ++m)
; #pragma unroll
;                 for (int n = 0; n < 2; ++n) acc[a][b][m][n] = (f32x4){0.f, 0.f, 0.f, 0.f};
;     bf16x8 At[4][2], B0[2][2], B1[2][2];
;     const char* cA = (const char*)g.A + (size_t)cur.pm * tstep; const char* cB = (const char*)g.Bt + (size_t)cur.pn * tstep;
;     PG8_STAGE(PG8_SB(0, 0), cB, voffB); PG8_STAGE(PG8_SA(0, 0), cA, voffA); PG8_STAGE(PG8_SB(0, 1), cB + hstep, voffB); PG8_STAGE(PG8_SA(0, 1), cA + hstep, voffA);
;     if (wr == 1) PG8_BAR;
;     PG8_WAIT_V(4); PG8_BAR;
;     PG8_STAGE(PG8_SB(1, 0), cB + kstep, voffB); PG8_STAGE(PG8_SA(1, 0), cA + kstep, voffA); PG8_STAGE(PG8_SB(1, 1), cB + hstep + kstep, voffB);
;     PG8_WAIT_V(6); PG8_BAR;
.LBB0_853:
	s_or_b64 exec, exec, s[2:3]
	v_mov_b32_e32 v9, v158
	s_waitcnt lgkmcnt(0)
	s_barrier
	s_and_b64 vcc, exec, s[4:5]
	v_readfirstlane_b32 s10, v9
	s_cbranch_vccnz .LBB0_869
	v_lshlrev_b32_e32 v0, 4, v9
	v_add_u32_e32 v1, 0x2000, v0
	v_ashrrev_i32_e32 v2, 31, v1
	v_lshrrev_b32_e32 v2, 22, v2
	v_add_u32_e32 v2, v1, v2
	v_ashrrev_i32_e32 v8, 10, v2
	v_mul_i32_i24_e32 v2, 0x400, v8
	v_sub_u32_e32 v1, v1, v2
	v_lshrrev_b32_e32 v2, 4, v1
	v_bitop3_b32 v1, v2, v1, 32 bitop3:0x6c
	v_ashrrev_i32_e32 v2, 31, v1
	v_lshrrev_b32_e32 v2, 26, v2
	v_add_u32_e32 v2, v1, v2
	v_lshlrev_b32_e32 v3, 3, v8
	v_ashrrev_i32_e32 v10, 6, v2
	v_and_b32_e32 v3, -16, v3
	v_add_u32_e32 v3, v10, v3
	v_and_b32_e32 v4, 3, v10
	s_mov_b32 s3, 0x7fffe0
	v_lshrrev_b32_e32 v5, 2, v3
	v_lshlrev_b32_e32 v6, 1, v3
	v_and_b32_e32 v2, 0xc0, v2
	v_and_or_b32 v4, v3, s3, v4
	v_and_b32_e32 v5, 4, v5
	v_and_b32_e32 v6, 24, v6
	v_sub_u32_e32 v1, v1, v2
	v_mov_b32_e32 v2, 1
	v_or3_b32 v4, v4, v5, v6
	v_lshlrev_b32_e32 v5, 5, v8
	v_ashrrev_i16_sdwa v1, v2, sext(v1) dst_sel:DWORD dst_unused:UNUSED_PAD src0_sel:DWORD src1_sel:BYTE_0
	s_movk_i32 s6, 0x1600
	v_and_b32_e32 v11, 32, v5
	v_bfe_i32 v12, v1, 0, 16
	v_mul_u32_u24_e32 v4, 0x1600, v4
	v_add_u32_e32 v1, v11, v12
	v_mul_lo_u32 v3, v3, s6
	v_add_lshl_u32 v128, v4, v1, 1
	v_add_lshl_u32 v130, v1, v3, 1
	v_bfe_i32 v1, v9, 27, 1
	v_lshrrev_b32_e32 v1, 22, v1
	v_add_u32_e32 v1, v0, v1
	v_and_b32_e32 v1, 0xfffffc00, v1
	v_sub_u32_e32 v0, v0, v1
	v_lshrrev_b32_e32 v1, 4, v0
	v_bitop3_b32 v1, v1, v0, 32 bitop3:0x6c
	v_ashrrev_i32_e32 v0, 31, v0
	v_lshrrev_b32_e32 v0, 26, v0
	v_add_u32_e32 v0, v1, v0
	v_ashrrev_i32_e32 v13, 6, v0
	v_ashrrev_i32_e32 v0, 31, v9
	v_lshrrev_b32_e32 v0, 26, v0
	v_add_u32_e32 v0, v9, v0
	v_ashrrev_i32_e32 v14, 6, v0
	v_lshlrev_b32_e32 v0, 3, v14
	s_add_u32 s11, s16, 0x6e00000
	v_and_b32_e32 v0, -16, v0
	s_addc_u32 s22, s17, 0
	v_add_u32_e32 v0, v13, v0
	v_and_b32_e32 v3, 3, v13
	s_ashr_i32 s27, s12, 31
	v_and_or_b32 v3, v0, s3, v3
	s_lshr_b32 s3, s27, 26
	s_add_i32 s3, s12, s3
	s_ashr_i32 s8, s3, 6
	s_and_b32 s3, s3, 0xffc0
	s_sub_i32 s3, s12, s3
	s_lshl_b32 s9, s8, 3
	s_bfe_i32 s8, s3, 0x80000
	v_lshrrev_b32_e32 v4, 2, v0
	v_lshlrev_b32_e32 v5, 1, v0
	s_bfe_u32 s8, s8, 0x3000c
	v_and_b32_e32 v4, 4, v4
	v_and_b32_e32 v5, 24, v5
	s_add_i32 s28, s3, s8
	v_or3_b32 v3, v3, v4, v5
	v_lshlrev_b32_e32 v4, 5, v14
	s_bfe_i32 s8, s28, 0x80000
	s_and_b32 s28, s28, 0xf8
	v_and_b32_e32 v15, 32, v4
	v_mul_i32_i24_e32 v4, 64, v13
	s_sext_i32_i16 s29, s8
	s_sub_i32 s3, s3, s28
	s_ashr_i32 s2, s10, 6
	v_sub_u32_e32 v1, v1, v4
	s_sext_i32_i8 s3, s3
	s_ashr_i32 s28, s29, 3
	s_ashr_i32 s7, s10, 8
	s_lshl_b32 s23, s2, 10
	v_ashrrev_i16_sdwa v1, v2, sext(v1) dst_sel:DWORD dst_unused:UNUSED_PAD src0_sel:DWORD src1_sel:BYTE_0
	s_lshr_b32 s8, s29, 3
	s_add_i32 s63, s9, s3
	s_mul_hi_i32 s29, s28, 0x2c0000
	s_mul_i32 s28, s28, 0x2c0000
	v_bfe_i32 v16, v1, 0, 16
	s_add_u32 s44, s11, s28
	v_mul_u32_u24_e32 v3, 0x1600, v3
	v_add_u32_e32 v1, v15, v16
	s_addc_u32 s45, s22, s29
	s_add_i32 s28, s23, 0
	v_add_lshl_u32 v132, v3, v1, 1
	s_add_i32 m0, s28, 0x10000
	s_mul_i32 s9, s63, 0x2c0000
	global_load_lds_dwordx4 v132, s[44:45]
	s_add_i32 m0, s28, 0x12000
	v_mul_lo_u32 v0, v0, s6
	s_mul_hi_i32 s3, s63, 0x2c0000
	s_add_u32 s42, s20, s9
	v_add_lshl_u32 v134, v1, v0, 1
	global_load_lds_dwordx4 v128, s[44:45]
	s_addc_u32 s43, s21, s3
	s_mov_b32 m0, s28
	s_add_i32 s29, s28, 0x2000
	global_load_lds_dwordx4 v134, s[42:43]
	s_mov_b32 m0, s29
	s_add_u32 s30, s44, 0x160000
	global_load_lds_dwordx4 v130, s[42:43]
	s_addc_u32 s31, s45, 0
	s_add_i32 m0, s28, 0x14000
	v_mov_b32_e32 v133, 0
	global_load_lds_dwordx4 v132, s[30:31]
	s_add_i32 m0, s28, 0x16000
	v_mov_b32_e32 v129, v133
	global_load_lds_dwordx4 v128, s[30:31]
	s_add_u32 s30, s42, 0x160000
	s_addc_u32 s31, s43, 0
	s_add_i32 s33, s28, 0x4000
	s_mov_b32 m0, s33
	s_add_i32 s50, s28, 0x6000
	global_load_lds_dwordx4 v134, s[30:31]
	s_mov_b32 m0, s50
	v_mov_b32_e32 v135, v133
	global_load_lds_dwordx4 v130, s[30:31]
	v_mov_b32_e32 v131, v133
	s_mov_b32 s51, 0
	v_lshl_add_u64 v[6:7], s[44:45], 0, v[132:133]
	v_lshl_add_u64 v[4:5], s[44:45], 0, v[128:129]
	v_lshl_add_u64 v[2:3], s[42:43], 0, v[134:135]
	v_lshl_add_u64 v[0:1], s[42:43], 0, v[130:131]
	s_cmp_lg_u32 s7, 1
	s_mov_b32 s9, 0x16000
	s_setprio 1
	s_cbranch_scc1 .LBB0_856
	s_barrier
	s_setprio 0

; __device__ __forceinline__ int fresh_tid() { int t = threadIdx.x; asm volatile("" : "+v"(t)); return t; }
; #define PG8_STAGE(bufoff, gbase, voff) do { _Pragma("unroll") for (int _i = 0; _i < 2; ++_i) \
;         __builtin_amdgcn_global_load_lds((const unsigned*)((const char*)(gbase) + (voff)[_i]), (LAS unsigned*)(lds + (bufoff) + ldsw + _i * 8192), 16, 0, 0); } while (0)
; #define PG8_WAIT_V(n) asm volatile("s_waitcnt vmcnt(" #n ")" ::: "memory")
; #define PG8_BAR __builtin_amdgcn_s_barrier()
; template <class Epi>
; __device__ __forceinline__ void gemm_phase(LAS unsigned char* lds, const Gemm g, const StaticOrder& S, const Epi& E) {
;     const int tid = fresh_tid(), wid = __builtin_amdgcn_readfirstlane(tid >> 6), lane = tid & 63, wr = wid >> 2, wc = wid & 3, fr = lane & 15, fq = lane >> 4;
;     const int K = g.K, nt = K / BK;
;     unsigned voffA[2], voffB[2];
; #pragma unroll
;     for (int i = 0; i < 2; ++i) { int R, C; stage_rc(tid * 16 + i * 8192, R, C); const int Rb = (R & ~31) + perm32(R & 31);
;         voffA[i] = (unsigned)(R * K + C) * 2u; voffB[i] = (unsigned)(Rb * K + C) * 2u; }
;     const size_t kstep = (size_t)(BK * 2);
;     const size_t hstep = (size_t)HALF * K * 2;
;     const size_t tstep = 2 * hstep;
;     const unsigned ldsw = (unsigned)wid * 1024u;
;     const int aoff = lds_byte(wr * 64 + fr, fq * 8), boff = lds_byte(wc * 32 + fr, fq * 8);
;     ...
;     Unit cur, nxt; int ui = 0;
;     if (!S.next(0, cur)) return;
;     f32x4 acc[2][2][4][2];
; #pragma unroll
;     for (int a = 0; a < 2; ++a)
; #pragma unroll
;         for (int b = 0; b < 2; ++b)
; #pragma unroll
;             for (int m = 0; m < 4; ++m)
; #pragma unroll
;                 for (int n = 0; n < 2; ++n) acc[a][b][m][n] = (f32x4){0.f, 0.f, 0.f, 0.f};
;     bf16x8 At[4][2], B0[2][2], B1[2][2];
;     const char* cA = (const char*)g.A + (size_t)cur.pm * tstep; const char* cB = (const char*)g.Bt + (size_t)cur.pn * tstep;
;     PG8_STAGE(PG8_SB(0, 0), cB, voffB); PG8_STAGE(PG8_SA(0, 0), cA, voffA); PG8_STAGE(PG8_SB(0, 1), cB + hstep, voffB); PG8_STAGE(PG8_SA(0, 1), cA + hstep, voffA);
;     if (wr == 1) PG8_BAR;
;     PG8_WAIT_V(4); PG8_BAR;
;     PG8_STAGE(PG8_SB(1, 0), cB + kstep, voffB); PG8_STAGE(PG8_SA(1, 0), cA + kstep, voffA); PG8_STAGE(PG8_SB(1, 1), cB + hstep + kstep, voffB);
;     PG8_WAIT_V(6); PG8_BAR;
.LBB0_980:
	s_or_b64 exec, exec, s[2:3]
	v_mov_b32_e32 v8, v158
	s_waitcnt lgkmcnt(0)
	s_barrier
	s_and_b64 vcc, exec, s[4:5]
	v_readfirstlane_b32 s10, v8
	s_cbranch_vccnz .LBB0_992
	v_lshlrev_b32_e32 v0, 4, v8
	v_add_u32_e32 v1, 0x2000, v0
	v_ashrrev_i32_e32 v2, 31, v1
	v_lshrrev_b32_e32 v2, 22, v2
	v_add_u32_e32 v2, v1, v2
	v_ashrrev_i32_e32 v2, 10, v2
	v_mul_i32_i24_e32 v4, 0x400, v2
	v_sub_u32_e32 v1, v1, v4
	v_lshrrev_b32_e32 v4, 4, v1
	v_bitop3_b32 v1, v4, v1, 32 bitop3:0x6c
	v_ashrrev_i32_e32 v4, 31, v1
	v_lshrrev_b32_e32 v4, 26, v4
	v_add_u32_e32 v4, v1, v4
	v_readlane_b32 s2, v232, 9
	v_ashrrev_i32_e32 v5, 6, v4
	v_and_b32_e32 v4, 0xc0, v4
	s_lshl_b32 s2, s2, 9
	v_sub_u32_e32 v1, v1, v4
	v_mov_b32_e32 v4, 1
	s_add_u32 s2, s16, s2
	v_lshlrev_b32_e32 v3, 5, v2
	v_ashrrev_i16_sdwa v1, v4, sext(v1) dst_sel:DWORD dst_unused:UNUSED_PAD src0_sel:DWORD src1_sel:BYTE_0
	v_lshlrev_b32_e32 v2, 3, v2
	s_addc_u32 s3, s17, 0
	v_and_b32_e32 v3, 32, v3
	v_bfe_i32 v1, v1, 0, 16
	v_and_b32_e32 v2, -16, v2
	s_add_u32 s11, s2, 0xb100000
	v_add_u32_e32 v2, v5, v2
	v_add_lshl_u32 v1, v3, v1, 1
	v_bfe_i32 v3, v8, 27, 1
	s_addc_u32 s22, s3, 0
	v_and_b32_e32 v5, 3, v5
	s_mov_b32 s3, 0x7fffe0
	v_lshrrev_b32_e32 v6, 2, v2
	v_lshlrev_b32_e32 v7, 1, v2
	v_lshrrev_b32_e32 v3, 22, v3
	v_and_or_b32 v5, v2, s3, v5
	v_and_b32_e32 v6, 4, v6
	v_and_b32_e32 v7, 24, v7
	v_add_u32_e32 v3, v0, v3
	v_or3_b32 v5, v5, v6, v7
	v_and_b32_e32 v3, 0xfffffc00, v3
	v_lshl_add_u32 v128, v5, 9, v1
	v_lshl_add_u32 v130, v2, 9, v1
	v_ashrrev_i32_e32 v1, 31, v8
	v_sub_u32_e32 v0, v0, v3
	v_lshrrev_b32_e32 v1, 26, v1
	v_lshrrev_b32_e32 v3, 4, v0
	v_add_u32_e32 v1, v8, v1
	v_bitop3_b32 v3, v3, v0, 32 bitop3:0x6c
	v_ashrrev_i32_e32 v0, 31, v0
	v_ashrrev_i32_e32 v1, 6, v1
	v_lshrrev_b32_e32 v0, 26, v0
	v_lshlrev_b32_e32 v2, 5, v1
	v_add_u32_e32 v0, v3, v0
	v_lshlrev_b32_e32 v1, 3, v1
	s_add_u32 s23, s16, 0xac00000
	v_ashrrev_i32_e32 v0, 6, v0
	v_and_b32_e32 v1, -16, v1
	s_addc_u32 s27, s17, 0
	v_mul_i32_i24_e32 v5, 64, v0
	v_add_u32_e32 v1, v0, v1
	v_and_b32_e32 v0, 3, v0
	s_ashr_i32 s29, s12, 31
	v_and_or_b32 v0, v1, s3, v0
	s_lshr_b32 s3, s29, 26
	s_add_i32 s3, s12, s3
	s_ashr_i32 s6, s3, 6
	s_and_b32 s3, s3, 0xffc0
	s_sub_i32 s3, s12, s3
	s_lshl_b32 s8, s6, 3
	s_bfe_i32 s6, s3, 0x80000
	s_bfe_u32 s6, s6, 0x3000c
	s_add_i32 s9, s3, s6
	s_bfe_i32 s6, s9, 0x80000
	s_and_b32 s9, s9, 0xf8
	s_sub_i32 s3, s3, s9
	s_sext_i32_i16 s6, s6
	s_sext_i32_i8 s3, s3
	s_ashr_i32 s7, s10, 8
	s_lshr_b32 s6, s6, 3
	s_add_i32 s42, s8, s3
	s_ashr_i32 s2, s10, 6
	v_sub_u32_e32 v3, v3, v5
	s_ashr_i32 s43, s42, 31
	s_bfe_i64 s[30:31], s[6:7], 0x100000
	s_lshl_b32 s28, s2, 10
	v_ashrrev_i16_sdwa v3, v4, sext(v3) dst_sel:DWORD dst_unused:UNUSED_PAD src0_sel:DWORD src1_sel:BYTE_0
	v_lshrrev_b32_e32 v4, 2, v1
	v_lshlrev_b32_e32 v5, 1, v1
	s_lshl_b64 s[8:9], s[42:43], 17
	s_lshl_b64 s[30:31], s[30:31], 17
	v_and_b32_e32 v2, 32, v2
	v_bfe_i32 v3, v3, 0, 16
	v_and_b32_e32 v4, 4, v4
	v_and_b32_e32 v5, 24, v5
	s_add_u32 s44, s23, s30
	v_or3_b32 v0, v0, v4, v5
	v_add_lshl_u32 v2, v2, v3, 1
	s_addc_u32 s45, s27, s31
	s_add_i32 s33, s28, 0
	v_lshl_add_u32 v132, v0, 9, v2
	s_add_i32 m0, s33, 0x10000
	v_lshl_add_u32 v134, v1, 9, v2
	global_load_lds_dwordx4 v132, s[44:45]
	s_add_i32 m0, s33, 0x12000
	s_add_u32 s46, s11, s8
	global_load_lds_dwordx4 v128, s[44:45]
	s_addc_u32 s47, s22, s9
	s_mov_b32 m0, s33
	s_add_i32 s43, s33, 0x2000
	global_load_lds_dwordx4 v134, s[46:47]
	s_mov_b32 m0, s43
	s_add_u32 s8, s44, 0x10000
	global_load_lds_dwordx4 v130, s[46:47]
	s_addc_u32 s9, s45, 0
	s_add_i32 m0, s33, 0x14000
	v_mov_b32_e32 v133, 0
	global_load_lds_dwordx4 v132, s[8:9]
	s_add_i32 m0, s33, 0x16000
	v_mov_b32_e32 v129, v133
	global_load_lds_dwordx4 v128, s[8:9]
	s_add_u32 s8, s46, 0x10000
	s_addc_u32 s9, s47, 0
	s_add_i32 s62, s33, 0x4000
	s_mov_b32 m0, s62
	s_add_i32 s63, s33, 0x6000
	global_load_lds_dwordx4 v134, s[8:9]
	s_mov_b32 m0, s63
	v_mov_b32_e32 v135, v133
	global_load_lds_dwordx4 v130, s[8:9]
	v_mov_b32_e32 v131, v133
	s_mov_b32 s64, 0
	v_lshl_add_u64 v[6:7], s[44:45], 0, v[132:133]
	v_lshl_add_u64 v[4:5], s[44:45], 0, v[128:129]
	v_lshl_add_u64 v[2:3], s[46:47], 0, v[134:135]
	s_cmp_lg_u32 s7, 1
	v_lshl_add_u64 v[0:1], s[46:47], 0, v[130:131]
	s_setprio 1
	s_cbranch_scc1 .LBB0_983
	s_barrier
	s_setprio 0

; __device__ __forceinline__ int fresh_tid() { int t = threadIdx.x; asm volatile("" : "+v"(t)); return t; }
; #define PG8_STAGE(bufoff, gbase, voff) do { _Pragma("unroll") for (int _i = 0; _i < 2; ++_i) \
;         __builtin_amdgcn_global_load_lds((const unsigned*)((const char*)(gbase) + (voff)[_i]), (LAS unsigned*)(lds + (bufoff) + ldsw + _i * 8192), 16, 0, 0); } while (0)
; #define PG8_WAIT_V(n) asm volatile("s_waitcnt vmcnt(" #n ")" ::: "memory")
; #define PG8_BAR __builtin_amdgcn_s_barrier()
; template <class Epi>
; __device__ __forceinline__ void gemm_phase(LAS unsigned char* lds, const Gemm g, const StaticOrder& S, const Epi& E) {
;     const int tid = fresh_tid(), wid = __builtin_amdgcn_readfirstlane(tid >> 6), lane = tid & 63, wr = wid >> 2, wc = wid & 3, fr = lane & 15, fq = lane >> 4;
;     const int K = g.K, nt = K / BK;
;     unsigned voffA[2], voffB[2];
; #pragma unroll
;     for (int i = 0; i < 2; ++i) { int R, C; stage_rc(tid * 16 + i * 8192, R, C); const int Rb = (R & ~31) + perm32(R & 31);
;         voffA[i] = (unsigned)(R * K + C) * 2u; voffB[i] = (unsigned)(Rb * K + C) * 2u; }
;     const size_t kstep = (size_t)(BK * 2);
;     const size_t hstep = (size_t)HALF * K * 2;
;     const size_t tstep = 2 * hstep;
;     const unsigned ldsw = (unsigned)wid * 1024u;
;     const int aoff = lds_byte(wr * 64 + fr, fq * 8), boff = lds_byte(wc * 32 + fr, fq * 8);
;     ...
;     Unit cur, nxt; int ui = 0;
;     if (!S.next(0, cur)) return;
;     f32x4 acc[2][2][4][2];
; #pragma unroll
;     for (int a = 0; a < 2; ++a)
; #pragma unroll
;         for (int b = 0; b < 2; ++b)
; #pragma unroll
;             for (int m = 0; m < 4; ++m)
; #pragma unroll
;                 for (int n = 0; n < 2; ++n) acc[a][b][m][n] = (f32x4){0.f, 0.f, 0.f, 0.f};
;     bf16x8 At[4][2], B0[2][2], B1[2][2];
;     const char* cA = (const char*)g.A + (size_t)cur.pm * tstep; const char* cB = (const char*)g.Bt + (size_t)cur.pn * tstep;
;     PG8_STAGE(PG8_SB(0, 0), cB, voffB); PG8_STAGE(PG8_SA(0, 0), cA, voffA); PG8_STAGE(PG8_SB(0, 1), cB + hstep, voffB); PG8_STAGE(PG8_SA(0, 1), cA + hstep, voffA);
;     if (wr == 1) PG8_BAR;
;     PG8_WAIT_V(4); PG8_BAR;
;     PG8_STAGE(PG8_SB(1, 0), cB + kstep, voffB); PG8_STAGE(PG8_SA(1, 0), cA + kstep, voffA); PG8_STAGE(PG8_SB(1, 1), cB + hstep + kstep, voffB);
;     PG8_WAIT_V(6); PG8_BAR;
.LBB0_992:
	s_waitcnt vmcnt(0)
	v_mov_b32_e32 v9, v158
	s_waitcnt vmcnt(0) lgkmcnt(0)
	s_barrier
	s_and_b64 vcc, exec, s[4:5]
	v_readfirstlane_b32 s10, v9
	s_cbranch_vccnz .LBB0_1004
	v_lshlrev_b32_e32 v0, 4, v9
	v_add_u32_e32 v1, 0x2000, v0
	v_ashrrev_i32_e32 v2, 31, v1
	v_lshrrev_b32_e32 v2, 22, v2
	v_add_u32_e32 v2, v1, v2
	v_ashrrev_i32_e32 v8, 10, v2
	v_mul_i32_i24_e32 v2, 0x400, v8
	v_sub_u32_e32 v1, v1, v2
	v_lshrrev_b32_e32 v2, 4, v1
	v_bitop3_b32 v1, v2, v1, 32 bitop3:0x6c
	v_ashrrev_i32_e32 v2, 31, v1
	v_lshrrev_b32_e32 v2, 26, v2
	v_add_u32_e32 v2, v1, v2
	v_lshlrev_b32_e32 v3, 3, v8
	v_ashrrev_i32_e32 v10, 6, v2
	v_and_b32_e32 v3, -16, v3
	v_add_u32_e32 v3, v10, v3
	v_and_b32_e32 v4, 3, v10
	s_mov_b32 s2, 0xfffe0
	v_lshrrev_b32_e32 v5, 2, v3
	v_lshlrev_b32_e32 v6, 1, v3
	v_and_b32_e32 v2, 0xc0, v2
	v_and_or_b32 v4, v3, s2, v4
	v_and_b32_e32 v5, 4, v5
	v_and_b32_e32 v6, 24, v6
	v_sub_u32_e32 v1, v1, v2
	v_mov_b32_e32 v2, 1
	v_or3_b32 v4, v4, v5, v6
	v_lshlrev_b32_e32 v5, 5, v8
	v_ashrrev_i16_sdwa v1, v2, sext(v1) dst_sel:DWORD dst_unused:UNUSED_PAD src0_sel:DWORD src1_sel:BYTE_0
	v_and_b32_e32 v5, 32, v5
	v_bfe_i32 v11, v1, 0, 16
	v_add_lshl_u32 v1, v5, v11, 1
	v_lshl_add_u32 v128, v4, 12, v1
	v_lshl_add_u32 v130, v3, 12, v1
	v_bfe_i32 v1, v9, 27, 1
	v_lshrrev_b32_e32 v1, 22, v1
	v_add_u32_e32 v1, v0, v1
	v_and_b32_e32 v1, 0xfffffc00, v1
	v_sub_u32_e32 v0, v0, v1
	v_lshrrev_b32_e32 v1, 4, v0
	v_bitop3_b32 v1, v1, v0, 32 bitop3:0x6c
	v_ashrrev_i32_e32 v0, 31, v0
	v_lshrrev_b32_e32 v0, 26, v0
	v_add_u32_e32 v0, v1, v0
	v_ashrrev_i32_e32 v12, 6, v0
	v_ashrrev_i32_e32 v0, 31, v9
	v_lshrrev_b32_e32 v0, 26, v0
	v_add_u32_e32 v0, v9, v0
	v_ashrrev_i32_e32 v13, 6, v0
	v_lshlrev_b32_e32 v0, 3, v13
	s_add_u32 s11, s16, 0xa400000
	v_and_b32_e32 v0, -16, v0
	s_addc_u32 s22, s17, 0
	v_add_u32_e32 v0, v12, v0
	v_and_b32_e32 v3, 3, v12
	s_ashr_i32 s27, s12, 31
	v_and_or_b32 v3, v0, s2, v3
	s_lshr_b32 s2, s27, 26
	s_add_i32 s2, s12, s2
	s_ashr_i32 s3, s2, 6
	s_and_b32 s2, s2, 0xffc0
	s_sub_i32 s2, s12, s2
	s_bfe_i32 s5, s2, 0x80000
	s_bfe_u32 s5, s5, 0x3000c
	s_add_i32 s5, s2, s5
	s_bfe_i32 s6, s5, 0x80000
	s_and_b32 s5, s5, 0xf8
	v_lshrrev_b32_e32 v4, 2, v0
	v_lshlrev_b32_e32 v5, 1, v0
	s_sub_i32 s2, s2, s5
	v_and_b32_e32 v4, 4, v4
	v_and_b32_e32 v5, 24, v5
	s_lshl_b32 s3, s3, 3
	s_sext_i32_i16 s6, s6
	s_sext_i32_i8 s2, s2
	s_ashr_i32 s7, s10, 8
	v_or3_b32 v3, v3, v4, v5
	v_mul_i32_i24_e32 v5, 64, v12
	s_lshr_b32 s6, s6, 3
	s_add_i32 s44, s3, s2
	s_ashr_i32 s4, s10, 6
	v_sub_u32_e32 v1, v1, v5
	s_ashr_i32 s45, s44, 31
	s_bfe_i64 s[8:9], s[6:7], 0x100000
	s_lshl_b32 s23, s4, 10
	v_lshlrev_b32_e32 v4, 5, v13
	v_ashrrev_i16_sdwa v1, v2, sext(v1) dst_sel:DWORD dst_unused:UNUSED_PAD src0_sel:DWORD src1_sel:BYTE_0
	s_lshl_b64 s[2:3], s[44:45], 20
	s_lshl_b64 s[8:9], s[8:9], 20
	v_and_b32_e32 v4, 32, v4
	v_bfe_i32 v14, v1, 0, 16
	s_add_u32 s48, s11, s8
	v_add_lshl_u32 v1, v4, v14, 1
	s_addc_u32 s49, s22, s9
	s_add_i32 s28, s23, 0
	v_lshl_add_u32 v132, v3, 12, v1
	s_add_i32 m0, s28, 0x10000
	v_lshl_add_u32 v134, v0, 12, v1
	global_load_lds_dwordx4 v132, s[48:49]
	s_add_i32 m0, s28, 0x12000
	s_add_u32 s46, s97, s2
	global_load_lds_dwordx4 v128, s[48:49]
	s_addc_u32 s47, s94, s3
	s_mov_b32 m0, s28
	s_add_i32 s29, s28, 0x2000
	global_load_lds_dwordx4 v134, s[46:47]
	s_mov_b32 m0, s29
	s_add_u32 s2, s48, 0x80000
	global_load_lds_dwordx4 v130, s[46:47]
	s_addc_u32 s3, s49, 0
	s_add_i32 m0, s28, 0x14000
	v_mov_b32_e32 v133, 0
	global_load_lds_dwordx4 v132, s[2:3]
	s_add_i32 m0, s28, 0x16000
	v_mov_b32_e32 v129, v133
	global_load_lds_dwordx4 v128, s[2:3]
	s_add_u32 s2, s46, 0x80000
	s_addc_u32 s3, s47, 0
	s_add_i32 s33, s28, 0x4000
	s_mov_b32 m0, s33
	s_add_i32 s45, s28, 0x6000
	global_load_lds_dwordx4 v134, s[2:3]
	s_mov_b32 m0, s45
	v_mov_b32_e32 v135, v133
	global_load_lds_dwordx4 v130, s[2:3]
	v_mov_b32_e32 v131, v133
	s_mov_b32 s52, 0
	v_lshl_add_u64 v[6:7], s[48:49], 0, v[132:133]
	v_lshl_add_u64 v[4:5], s[48:49], 0, v[128:129]
	v_lshl_add_u64 v[2:3], s[46:47], 0, v[134:135]
	v_lshl_add_u64 v[0:1], s[46:47], 0, v[130:131]
	s_cmp_lg_u32 s7, 1
	s_mov_b64 s[2:3], 0x80000
	s_setprio 1
	s_cbranch_scc1 .LBB0_995
	s_barrier
	s_setprio 0
